# short-conv runs moved to workgroups 128..255 (one SSM1 unit less there)
# speedup vs baseline: 1.0091x; 1.0063x over previous
; __device__ __forceinline__ int ltid() { int t = threadIdx.x; asm volatile("" : "+v"(t)); return t; }
; __device__ __forceinline__ void conv_phase(const Params& P, int layer) {
;     const int tidx = ltid();
;     bf16_t* zb = (bf16_t*)(P.ws + OFF_ZB); const float* cw = P.conv_w + (size_t)layer * 3 * 512;
;     const int c8 = (tidx & 63) * 8;
;     f32x4 w[3][2];
; #pragma unroll
;     for (int d = 0; d < 3; ++d) { w[d][0] = *(const f32x4*)(cw + d * 512 + c8); w[d][1] = *(const f32x4*)(cw + d * 512 + c8 + 4); }
;     for (int run = blockIdx.x * 8 + (tidx >> 6); run < T_TOK / 16; run += gridDim.x * 8) {
;         const size_t t0 = (size_t)run * 16; const int s0 = (int)(t0 & 8191);
;         bf16_t* base = zb + t0 * ZW + c8;
.LBB0_578:
	s_mov_b64 s[6:7], s[4:5]
	v_mov_b32_e32 v0, v186
	v_readlane_b32 s2, v233, 2
	v_ashrrev_i32_e32 v2, 6, v0
	s_nop 0
	s_cmpk_lg_u32 s66, 0x800
	s_cbranch_scc1 .Lconv_keep
	s_sub_i32 s2, s2, 0x400
	s_movk_i32 s66, 0x400
	s_cmp_lt_i32 s2, 0
	s_cbranch_scc0 .Lconv_keep
	s_movk_i32 s2, 0x800
.Lconv_keep:
	v_add_u32_e32 v88, s2, v2
	s_movk_i32 s2, 0x800
	v_cmp_gt_i32_e32 vcc, s2, v88
	s_and_saveexec_b64 s[2:3], vcc
	s_cbranch_execz .LBB0_583
	s_load_dwordx2 s[4:5], s[6:7], 0x70
	s_nop 0
	s_load_dwordx2 s[6:7], s[6:7], 0xd0
	v_readlane_b32 s8, v231, 62
	s_mulk_i32 s8, 0x1800
	v_lshlrev_b32_e32 v0, 3, v0
	v_and_b32_e32 v32, 0x1f8, v0
	s_waitcnt lgkmcnt(0)
	s_add_u32 s4, s4, s8
	s_addc_u32 s5, s5, 0
	v_lshlrev_b32_e32 v0, 2, v32
	v_lshl_add_u64 v[2:3], s[4:5], 0, v[0:1]
	global_load_dwordx4 v[8:11], v0, s[4:5] offset:16
	global_load_dwordx4 v[12:15], v0, s[4:5]
	global_load_dwordx4 v[16:19], v0, s[4:5] offset:2064
	global_load_dwordx4 v[20:23], v0, s[4:5] offset:2048
	v_lshl_add_u64 v[28:29], v[2:3], 0, s[80:81]
	v_add_co_u32_e32 v2, vcc, 0x1000, v2
	v_lshlrev_b32_e32 v0, 1, v32
	s_nop 0
	v_addc_co_u32_e32 v3, vcc, 0, v3, vcc
	global_load_dwordx4 v[24:27], v[2:3], off
	s_nop 0
	global_load_dwordx4 v[28:31], v[28:29], off offset:16
	v_lshl_add_u64 v[2:3], s[6:7], 0, v[0:1]
	s_mov_b64 s[4:5], 0xae00000
	v_lshl_add_u64 v[2:3], v[2:3], 0, s[4:5]
	s_mov_b64 s[6:7], 0
	s_branch .LBB0_581
